# baseline (speedup 1.0000x reference)
; __device__ __forceinline__ float partner_sum(float v) { auto rr = __builtin_amdgcn_permlane32_swap(__float_as_uint(v), __float_as_uint(v), false, false); return __uint_as_float(rr[0]) + __uint_as_float(rr[1]); }
; __device__ __forceinline__ void df_unit_p128(ATT_LAS unsigned char* lds, const bf16_t* Q, const bf16_t* __restrict__ K, const bf16_t* __restrict__ V, bf16_t* O, int b, int h, int qb,
;                                              float lam, float post, const float* __restrict__ sub_g, const int wv) {
;     ...
;     if (mp == 0) {
;         float ss = 0.f;
; #pragma unroll
;         for (int d0 = 0; d0 < 4; ++d0)
; #pragma unroll
;             for (int i = 0; i < 4; ++i) { const f32x4 x2 = xch[(d0 * 4 + i) * 64];
; #pragma unroll
;                 for (int jj = 0; jj < 4; ++jj) { const float v = o[d0][4 * i + jj] * inv - x2[jj]; o[d0][4 * i + jj] = v; ss += v * v; } }
;         ss = partner_sum(ss);
;         const float rs = __builtin_amdgcn_rsqf(ss * (1.0f / 128.0f) + 1e-6f) * post;
;         bf16_t* Ow = O + (rowbase + q0 + rg * 32 + r32e) * DM + h * 128 + 4 * hie;
; #pragma unroll
;         for (int d0 = 0; d0 < 4; ++d0)
; #pragma unroll
;             for (int i = 0; i < 4; ++i) { const f32x4 g = *(const f32x4*)(sub_g + d0 * 32 + 8 * i + 4 * hie);
.LBB0_233:
	s_andn2_b64 vcc, exec, s[8:9]
	s_waitcnt vmcnt(0) lgkmcnt(0)
	s_barrier
	s_cbranch_vccnz .LBB0_235
	s_nop 0
	ds_read_b128 v[6:9], v2
	s_waitcnt lgkmcnt(0)
	v_fma_f32 v37, v66, v0, -v6
	v_fma_f32 v34, v67, v0, -v7
	v_fma_f32 v35, v68, v0, -v8
	v_fma_f32 v36, v69, v0, -v9
	ds_read_b128 v[6:9], v2 offset:1024
	v_mul_f32_e32 v3, v34, v34
	v_fmac_f32_e32 v3, v37, v37
	v_fmac_f32_e32 v3, v35, v35
	v_fmac_f32_e32 v3, v36, v36
	s_waitcnt lgkmcnt(0)
	v_fma_f32 v50, v70, v0, -v6
	v_fma_f32 v51, v71, v0, -v7
	v_fma_f32 v52, v72, v0, -v8
	v_fma_f32 v53, v73, v0, -v9
	ds_read_b128 v[6:9], v2 offset:2048
	v_fmac_f32_e32 v3, v50, v50
	v_fmac_f32_e32 v3, v51, v51
	v_fmac_f32_e32 v3, v52, v52
	v_fmac_f32_e32 v3, v53, v53
	s_waitcnt lgkmcnt(0)
	v_fma_f32 v58, v74, v0, -v6
	v_fma_f32 v54, v75, v0, -v7
	v_fma_f32 v46, v76, v0, -v8
	v_fma_f32 v42, v77, v0, -v9
	ds_read_b128 v[6:9], v2 offset:3072
	v_fmac_f32_e32 v3, v58, v58
	v_fmac_f32_e32 v3, v54, v54
	v_fmac_f32_e32 v3, v46, v46
	v_fmac_f32_e32 v3, v42, v42
	s_waitcnt lgkmcnt(0)
	v_fma_f32 v71, v78, v0, -v6
	v_fma_f32 v68, v79, v0, -v7
	v_fma_f32 v65, v80, v0, -v8
	v_fma_f32 v62, v81, v0, -v9
	ds_read_b128 v[6:9], v2 offset:4096
	v_fmac_f32_e32 v3, v71, v71
	v_fmac_f32_e32 v3, v68, v68
	v_fmac_f32_e32 v3, v65, v65
	v_fmac_f32_e32 v3, v62, v62
	s_waitcnt lgkmcnt(0)
	v_fma_f32 v59, v82, v0, -v6
	v_fma_f32 v55, v83, v0, -v7
	v_fma_f32 v47, v84, v0, -v8
	v_fma_f32 v43, v85, v0, -v9
	ds_read_b128 v[6:9], v2 offset:5120
	v_fmac_f32_e32 v3, v59, v59
	v_fmac_f32_e32 v3, v55, v55
	v_fmac_f32_e32 v3, v47, v47
	v_fmac_f32_e32 v3, v43, v43
	s_waitcnt lgkmcnt(0)
	v_fma_f32 v72, v86, v0, -v6
	v_fma_f32 v69, v87, v0, -v7
	v_fma_f32 v66, v88, v0, -v8
	v_fma_f32 v63, v89, v0, -v9
	ds_read_b128 v[6:9], v2 offset:6144
	v_fmac_f32_e32 v3, v72, v72
	v_fmac_f32_e32 v3, v69, v69
	v_fmac_f32_e32 v3, v66, v66
	v_fmac_f32_e32 v3, v63, v63
	s_waitcnt lgkmcnt(0)
	v_fma_f32 v60, v90, v0, -v6
	v_fma_f32 v56, v91, v0, -v7
	v_fma_f32 v48, v92, v0, -v8
	v_fma_f32 v44, v93, v0, -v9
	ds_read_b128 v[6:9], v2 offset:7168
	v_fmac_f32_e32 v3, v60, v60
	v_fmac_f32_e32 v3, v56, v56
	v_fmac_f32_e32 v3, v48, v48
	v_fmac_f32_e32 v3, v44, v44
	s_waitcnt lgkmcnt(0)
	v_fma_f32 v73, v94, v0, -v6
	v_fma_f32 v70, v95, v0, -v7
	v_fma_f32 v67, v96, v0, -v8
	v_fma_f32 v64, v97, v0, -v9
	ds_read_b128 v[6:9], v2 offset:8192
	v_fmac_f32_e32 v3, v73, v73
	v_fmac_f32_e32 v3, v70, v70
	v_fmac_f32_e32 v3, v67, v67
	v_fmac_f32_e32 v3, v64, v64
	s_waitcnt lgkmcnt(0)
	v_fma_f32 v61, v98, v0, -v6
	v_fma_f32 v57, v99, v0, -v7
	v_fma_f32 v49, v100, v0, -v8
	v_fma_f32 v45, v101, v0, -v9
	ds_read_b128 v[6:9], v2 offset:9216
	v_fmac_f32_e32 v3, v61, v61
	v_fmac_f32_e32 v3, v57, v57
	v_fmac_f32_e32 v3, v49, v49
	v_fmac_f32_e32 v3, v45, v45
	s_waitcnt lgkmcnt(0)
	v_fma_f32 v41, v102, v0, -v6
	v_fma_f32 v40, v103, v0, -v7
	v_fma_f32 v39, v104, v0, -v8
	v_fma_f32 v38, v105, v0, -v9
	ds_read_b128 v[6:9], v2 offset:10240
	v_fmac_f32_e32 v3, v41, v41
	v_fmac_f32_e32 v3, v40, v40
	v_fmac_f32_e32 v3, v39, v39
	v_fmac_f32_e32 v3, v38, v38
	s_waitcnt lgkmcnt(0)
	v_fma_f32 v33, v106, v0, -v6
	v_fma_f32 v32, v107, v0, -v7
	v_fma_f32 v31, v108, v0, -v8
	v_fma_f32 v30, v109, v0, -v9
	ds_read_b128 v[6:9], v2 offset:11264
	v_fmac_f32_e32 v3, v33, v33
	v_fmac_f32_e32 v3, v32, v32
	v_fmac_f32_e32 v3, v31, v31
	v_fmac_f32_e32 v3, v30, v30
	s_waitcnt lgkmcnt(0)
	v_fma_f32 v29, v110, v0, -v6
	v_fma_f32 v28, v111, v0, -v7
	v_fma_f32 v27, v112, v0, -v8
	v_fma_f32 v26, v113, v0, -v9
	ds_read_b128 v[6:9], v2 offset:12288
	v_fmac_f32_e32 v3, v29, v29
	v_fmac_f32_e32 v3, v28, v28
	v_fmac_f32_e32 v3, v27, v27
	v_fmac_f32_e32 v3, v26, v26
	s_waitcnt lgkmcnt(0)
	v_fma_f32 v25, v114, v0, -v6
	v_fma_f32 v24, v115, v0, -v7
	v_fma_f32 v23, v116, v0, -v8
	v_fma_f32 v22, v117, v0, -v9
	ds_read_b128 v[6:9], v2 offset:13312
	v_fmac_f32_e32 v3, v25, v25
	v_fmac_f32_e32 v3, v24, v24
	v_fmac_f32_e32 v3, v23, v23
	v_fmac_f32_e32 v3, v22, v22
	s_waitcnt lgkmcnt(0)
	v_fma_f32 v21, v118, v0, -v6
	v_fma_f32 v20, v119, v0, -v7
	v_fma_f32 v19, v120, v0, -v8
	v_fma_f32 v18, v121, v0, -v9
	ds_read_b128 v[6:9], v2 offset:14336
	v_fmac_f32_e32 v3, v21, v21
	v_fmac_f32_e32 v3, v20, v20
	v_fmac_f32_e32 v3, v19, v19
	v_fmac_f32_e32 v3, v18, v18
	s_waitcnt lgkmcnt(0)
	v_fma_f32 v17, v122, v0, -v6
	v_fma_f32 v16, v123, v0, -v7
	v_fma_f32 v15, v124, v0, -v8
	v_fma_f32 v14, v125, v0, -v9
	ds_read_b128 v[6:9], v2 offset:15360
	v_fmac_f32_e32 v3, v17, v17
	v_fmac_f32_e32 v3, v16, v16
	v_fmac_f32_e32 v3, v15, v15
	v_fmac_f32_e32 v3, v14, v14
	s_waitcnt lgkmcnt(0)
	v_fma_f32 v13, v126, v0, -v6
	v_fmac_f32_e32 v3, v13, v13
	v_fma_f32 v12, v127, v0, -v7
	v_fmac_f32_e32 v3, v12, v12
	v_fma_f32 v10, v128, v0, -v8
	v_fmac_f32_e32 v3, v10, v10
	v_fma_f32 v0, v129, v0, -v9
	v_fmac_f32_e32 v3, v0, v0
	v_mov_b32_e32 v2, v3
	s_nop 1
	v_permlane32_swap_b32_e32 v3, v2
	v_add_f32_e32 v2, v3, v2
	v_fmamk_f32 v2, v2, 0x3c000000, v240
	v_rsq_f32_e32 v2, v2
	v_mov_b32_e32 v3, s27
	v_mul_f32_e32 v11, v245, v2
	v_and_or_b32 v2, v4, 31, s26
	v_ashrrev_i32_e32 v4, 3, v4
	v_lshlrev_b64 v[2:3], 11, v[2:3]
	v_and_b32_e32 v4, -4, v4
	v_lshl_add_u64 v[2:3], s[56:57], 0, v[2:3]
	v_ashrrev_i32_e32 v5, 31, v4
	v_lshl_add_u64 v[2:3], v[2:3], 0, s[54:55]
	v_lshl_add_u64 v[8:9], v[4:5], 2, s[0:1]
	v_lshl_add_u64 v[6:7], v[4:5], 1, v[2:3]
	global_load_dwordx4 v[130:133], v[8:9], off
	global_load_dwordx4 v[134:137], v[8:9], off offset:32
	global_load_dwordx4 v[138:141], v[8:9], off offset:64
	global_load_dwordx4 v[142:145], v[8:9], off offset:96
	global_load_dwordx4 v[146:149], v[8:9], off offset:128
	global_load_dwordx4 v[150:153], v[8:9], off offset:160
	global_load_dwordx4 v[154:157], v[8:9], off offset:192
	global_load_dwordx4 v[158:161], v[8:9], off offset:224
	global_load_dwordx4 v[162:165], v[8:9], off offset:256
	global_load_dwordx4 v[166:169], v[8:9], off offset:288
	global_load_dwordx4 v[170:173], v[8:9], off offset:320
	global_load_dwordx4 v[174:177], v[8:9], off offset:352
	global_load_dwordx4 v[178:181], v[8:9], off offset:384
	global_load_dwordx4 v[182:185], v[8:9], off offset:416
	global_load_dwordx4 v[186:189], v[8:9], off offset:448
	global_load_dwordx4 v[190:193], v[8:9], off offset:480
	s_nop 0
	v_mul_f32_e32 v37, v37, v11
	v_mul_f32_e32 v34, v34, v11
	v_mul_f32_e32 v33, v33, v11
	v_mul_f32_e32 v32, v32, v11
	v_mul_f32_e32 v29, v29, v11
	v_mul_f32_e32 v28, v28, v11
	v_mul_f32_e32 v25, v25, v11
	v_mul_f32_e32 v24, v24, v11
	v_mul_f32_e32 v21, v21, v11
	v_mul_f32_e32 v20, v20, v11
	v_mul_f32_e32 v17, v17, v11
	v_mul_f32_e32 v16, v16, v11
	v_mul_f32_e32 v0, v0, v11
	s_waitcnt vmcnt(0)
; __device__ __forceinline__ unsigned cvtpk(float lo, float hi) { unsigned r; asm volatile("v_cvt_pk_bf16_f32 %0, %1, %2" : "=v"(r) : "v"(lo), "v"(hi)); return r; }
; __device__ __forceinline__ void df_unit_p128(ATT_LAS unsigned char* lds, const bf16_t* Q, const bf16_t* __restrict__ K, const bf16_t* __restrict__ V, bf16_t* O, int b, int h, int qb,
;                                              float lam, float post, const float* __restrict__ sub_g, const int wv) {
;     ...
;         const float rs = __builtin_amdgcn_rsqf(ss * (1.0f / 128.0f) + 1e-6f) * post;
;         bf16_t* Ow = O + (rowbase + q0 + rg * 32 + r32e) * DM + h * 128 + 4 * hie;
; #pragma unroll
;         for (int d0 = 0; d0 < 4; ++d0)
; #pragma unroll
;             for (int i = 0; i < 4; ++i) { const f32x4 g = *(const f32x4*)(sub_g + d0 * 32 + 8 * i + 4 * hie);
;                 u32x2 w; w.x = cvtpk(o[d0][4 * i] * rs * g[0], o[d0][4 * i + 1] * rs * g[1]); w.y = cvtpk(o[d0][4 * i + 2] * rs * g[2], o[d0][4 * i + 3] * rs * g[3]);
;                 *(u32x2*)(Ow + d0 * 32 + 8 * i) = w; }
	v_mul_f32_e32 v2, v130, v37
	v_mul_f32_e32 v3, v131, v34
	v_cvt_pk_bf16_f32 v2, v2, v3
	v_mul_f32_e32 v3, v35, v11
	v_mul_f32_e32 v3, v132, v3
	v_mul_f32_e32 v4, v36, v11
	v_mul_f32_e32 v4, v133, v4
	v_cvt_pk_bf16_f32 v3, v3, v4
	global_store_dwordx2 v[6:7], v[2:3], off
	v_mul_f32_e32 v34, v50, v11
	v_mul_f32_e32 v2, v134, v34
	v_mul_f32_e32 v34, v51, v11
	v_mul_f32_e32 v3, v135, v34
	v_cvt_pk_bf16_f32 v2, v2, v3
	v_mul_f32_e32 v3, v52, v11
	v_mul_f32_e32 v3, v136, v3
	v_mul_f32_e32 v4, v53, v11
	v_mul_f32_e32 v4, v137, v4
	v_cvt_pk_bf16_f32 v3, v3, v4
	global_store_dwordx2 v[6:7], v[2:3], off offset:16
	v_mul_f32_e32 v34, v58, v11
	v_mul_f32_e32 v2, v34, v138
	v_mul_f32_e32 v34, v54, v11
	v_mul_f32_e32 v3, v34, v139
	v_cvt_pk_bf16_f32 v2, v2, v3
	v_mul_f32_e32 v3, v46, v11
	v_mul_f32_e32 v3, v3, v140
	v_mul_f32_e32 v4, v42, v11
	v_mul_f32_e32 v4, v4, v141
	v_cvt_pk_bf16_f32 v3, v3, v4
	global_store_dwordx2 v[6:7], v[2:3], off offset:32
	v_mul_f32_e32 v34, v71, v11
	v_mul_f32_e32 v2, v34, v142
	v_mul_f32_e32 v34, v68, v11
	v_mul_f32_e32 v3, v34, v143
	v_cvt_pk_bf16_f32 v2, v2, v3
	v_mul_f32_e32 v3, v65, v11
	v_mul_f32_e32 v3, v3, v144
	v_mul_f32_e32 v4, v62, v11
	v_mul_f32_e32 v4, v4, v145
	v_cvt_pk_bf16_f32 v3, v3, v4
	global_store_dwordx2 v[6:7], v[2:3], off offset:48
	v_mul_f32_e32 v34, v59, v11
	v_mul_f32_e32 v2, v34, v146
	v_mul_f32_e32 v34, v55, v11
	v_mul_f32_e32 v3, v34, v147
	v_cvt_pk_bf16_f32 v2, v2, v3
	v_mul_f32_e32 v3, v47, v11
	v_mul_f32_e32 v3, v3, v148
	v_mul_f32_e32 v4, v43, v11
	v_mul_f32_e32 v4, v4, v149
	v_cvt_pk_bf16_f32 v3, v3, v4
	global_store_dwordx2 v[6:7], v[2:3], off offset:64
	v_mul_f32_e32 v34, v72, v11
	v_mul_f32_e32 v2, v34, v150
	v_mul_f32_e32 v34, v69, v11
	v_mul_f32_e32 v3, v34, v151
	v_cvt_pk_bf16_f32 v2, v2, v3
	v_mul_f32_e32 v3, v66, v11
	v_mul_f32_e32 v3, v3, v152
	v_mul_f32_e32 v4, v63, v11
	v_mul_f32_e32 v4, v4, v153
	v_cvt_pk_bf16_f32 v3, v3, v4
	global_store_dwordx2 v[6:7], v[2:3], off offset:80
	v_mul_f32_e32 v34, v60, v11
	v_mul_f32_e32 v2, v34, v154
	v_mul_f32_e32 v34, v56, v11
	v_mul_f32_e32 v3, v34, v155
	v_cvt_pk_bf16_f32 v2, v2, v3
	v_mul_f32_e32 v3, v48, v11
	v_mul_f32_e32 v3, v3, v156
	v_mul_f32_e32 v4, v44, v11
	v_mul_f32_e32 v4, v4, v157
	v_cvt_pk_bf16_f32 v3, v3, v4
	global_store_dwordx2 v[6:7], v[2:3], off offset:96
	v_mul_f32_e32 v34, v73, v11
	v_mul_f32_e32 v2, v34, v158
	v_mul_f32_e32 v34, v70, v11
	v_mul_f32_e32 v3, v34, v159
	v_cvt_pk_bf16_f32 v2, v2, v3
	v_mul_f32_e32 v3, v67, v11
	v_mul_f32_e32 v3, v3, v160
	v_mul_f32_e32 v4, v64, v11
	v_mul_f32_e32 v4, v4, v161
	v_cvt_pk_bf16_f32 v3, v3, v4
	global_store_dwordx2 v[6:7], v[2:3], off offset:112
	v_mul_f32_e32 v34, v61, v11
	v_mul_f32_e32 v2, v34, v162
	v_mul_f32_e32 v34, v57, v11
	v_mul_f32_e32 v3, v34, v163
	v_cvt_pk_bf16_f32 v2, v2, v3
	v_mul_f32_e32 v3, v49, v11
	v_mul_f32_e32 v3, v3, v164
	v_mul_f32_e32 v4, v45, v11
	v_mul_f32_e32 v4, v4, v165
	v_cvt_pk_bf16_f32 v3, v3, v4
	global_store_dwordx2 v[6:7], v[2:3], off offset:128
	v_mul_f32_e32 v34, v41, v11
	v_mul_f32_e32 v2, v34, v166
	v_mul_f32_e32 v34, v40, v11
	v_mul_f32_e32 v3, v34, v167
	v_cvt_pk_bf16_f32 v2, v2, v3
	v_mul_f32_e32 v3, v39, v11
	v_mul_f32_e32 v3, v3, v168
	v_mul_f32_e32 v4, v38, v11
	v_mul_f32_e32 v4, v4, v169
	v_cvt_pk_bf16_f32 v3, v3, v4
	global_store_dwordx2 v[6:7], v[2:3], off offset:144
	v_mul_f32_e32 v2, v33, v170
	v_mul_f32_e32 v3, v32, v171
	v_cvt_pk_bf16_f32 v2, v2, v3
	v_mul_f32_e32 v3, v31, v11
	v_mul_f32_e32 v3, v3, v172
	v_mul_f32_e32 v4, v30, v11
	v_mul_f32_e32 v4, v4, v173
	v_cvt_pk_bf16_f32 v3, v3, v4
	global_store_dwordx2 v[6:7], v[2:3], off offset:160
	v_mul_f32_e32 v2, v29, v174
	v_mul_f32_e32 v3, v28, v175
	v_cvt_pk_bf16_f32 v2, v2, v3
	v_mul_f32_e32 v3, v27, v11
	v_mul_f32_e32 v3, v3, v176
	v_mul_f32_e32 v4, v26, v11
	v_mul_f32_e32 v4, v4, v177
	v_cvt_pk_bf16_f32 v3, v3, v4
	global_store_dwordx2 v[6:7], v[2:3], off offset:176
	v_mul_f32_e32 v2, v25, v178
	v_mul_f32_e32 v3, v24, v179
	v_cvt_pk_bf16_f32 v2, v2, v3
	v_mul_f32_e32 v3, v23, v11
	v_mul_f32_e32 v3, v3, v180
	v_mul_f32_e32 v4, v22, v11
	v_mul_f32_e32 v4, v4, v181
	v_cvt_pk_bf16_f32 v3, v3, v4
	global_store_dwordx2 v[6:7], v[2:3], off offset:192
	v_mul_f32_e32 v2, v21, v182
	v_mul_f32_e32 v3, v20, v183
	v_cvt_pk_bf16_f32 v2, v2, v3
	v_mul_f32_e32 v3, v19, v11
	v_mul_f32_e32 v3, v3, v184
	v_mul_f32_e32 v4, v18, v11
	v_mul_f32_e32 v4, v4, v185
	v_cvt_pk_bf16_f32 v3, v3, v4
	global_store_dwordx2 v[6:7], v[2:3], off offset:208
	v_mul_f32_e32 v2, v17, v186
	v_mul_f32_e32 v3, v16, v187
	v_cvt_pk_bf16_f32 v2, v2, v3
	v_mul_f32_e32 v3, v15, v11
	v_mul_f32_e32 v3, v3, v188
	v_mul_f32_e32 v4, v14, v11
	v_mul_f32_e32 v4, v4, v189
	v_cvt_pk_bf16_f32 v3, v3, v4
	global_store_dwordx2 v[6:7], v[2:3], off offset:224
	v_mul_f32_e32 v8, v13, v11
	v_mul_f32_e32 v2, v8, v190
	v_mul_f32_e32 v8, v12, v11
	v_mul_f32_e32 v3, v8, v191
	v_cvt_pk_bf16_f32 v2, v2, v3
	v_mul_f32_e32 v3, v10, v11
	v_mul_f32_e32 v3, v3, v192
	v_mul_f32_e32 v0, v0, v193
	v_cvt_pk_bf16_f32 v3, v3, v0
	global_store_dwordx2 v[6:7], v[2:3], off offset:240
	s_nop 0
